# P8: non-temporal stores for the two F row-tile groups written first (134 MB that cannot stay in MALL until P9 reads them); the rest of F and h2 keep the cache
# speedup vs baseline: 1.0185x; 1.0105x over previous
.LBB0_898:
	s_mul_i32 s98, s26, 0xccd
	s_lshr_b32 s98, s98, 16
	s_mul_i32 s98, s98, 20
	s_sub_i32 s98, s26, s98
	s_cmp_ge_u32 s98, 12
	s_cselect_b32 s99, 1, 0
	v_max_f32_e32 v125, v125, v125
	v_max_f32_e32 v124, v124, v124
	v_max_f32_e32 v127, v127, v127
	v_max_f32_e32 v126, v126, v126
	v_max_f32_e32 v121, v121, v121
	v_max_f32_e32 v120, v120, v120
	v_max_f32_e32 v123, v123, v123
	v_max_f32_e32 v122, v122, v122
	v_max_f32_e32 v125, 0, v125
	v_max_f32_e32 v124, 0, v124
	v_max_f32_e32 v127, 0, v127
	v_max_f32_e32 v126, 0, v126
	v_max_f32_e32 v121, 0, v121
	v_max_f32_e32 v120, 0, v120
	v_max_f32_e32 v123, 0, v123
	v_max_f32_e32 v122, 0, v122
	v_pk_mul_f32 v[126:127], v[126:127], v[126:127]
	v_pk_mul_f32 v[124:125], v[124:125], v[124:125]
	v_pk_mul_f32 v[152:153], v[122:123], v[122:123]
	v_pk_mul_f32 v[122:123], v[120:121], v[120:121]
	s_nop 7
	v_cvt_pk_bf16_f32 v120, v124, v125
	v_cvt_pk_bf16_f32 v121, v126, v127
	v_cvt_pk_bf16_f32 v122, v122, v123
	v_cvt_pk_bf16_f32 v123, v152, v153
	v_max_f32_e32 v117, 0, v117
	v_max_f32_e32 v116, 0, v116
	v_max_f32_e32 v119, 0, v119
	v_max_f32_e32 v118, 0, v118
	v_max_f32_e32 v113, 0, v113
	v_max_f32_e32 v112, 0, v112
	v_max_f32_e32 v115, 0, v115
	v_max_f32_e32 v114, 0, v114
	ds_write_b128 v147, v[120:123]
	v_pk_mul_f32 v[118:119], v[118:119], v[118:119]
	v_pk_mul_f32 v[116:117], v[116:117], v[116:117]
	v_pk_mul_f32 v[120:121], v[114:115], v[114:115]
	v_pk_mul_f32 v[114:115], v[112:113], v[112:113]
	v_lshl_add_u32 v150, s26, 8, v143
	v_cvt_pk_bf16_f32 v112, v116, v117
	v_cvt_pk_bf16_f32 v113, v118, v119
	v_cvt_pk_bf16_f32 v114, v114, v115
	v_cvt_pk_bf16_f32 v115, v120, v121
	v_ashrrev_i32_e32 v151, 31, v150
	ds_write_b128 v147, v[112:115] offset:64
	v_lshlrev_b64 v[150:151], 13, v[150:151]
	s_lshl_b32 s28, s61, 8
	ds_read_b128 v[114:117], v148
	ds_read_b128 v[118:121], v148 offset:1152
	v_lshl_add_u64 v[150:151], s[4:5], 0, v[150:151]
	s_ashr_i32 s29, s28, 31
	v_lshl_add_u64 v[112:113], s[28:29], 1, v[150:151]
	v_lshl_add_u64 v[112:113], v[112:113], 0, s[8:9]
	v_lshl_add_u64 v[112:113], v[112:113], 0, v[132:133]
	s_waitcnt lgkmcnt(0)
	s_cmp_lg_u32 s99, 0
	s_cbranch_scc1 .Lf8nt_0
	global_store_dwordx4 v[112:113], v[114:117], off
	s_branch .Lf8d_0
.Lf8nt_0:
	global_store_dwordx4 v[112:113], v[114:117], off nt
.Lf8d_0:
	s_nop 1
	v_add_co_u32_e32 v114, vcc, s42, v112
	s_nop 5
	v_addc_co_u32_e32 v115, vcc, 0, v113, vcc
	v_max_f32_e32 v109, 0, v109
	v_max_f32_e32 v108, 0, v108
	v_max_f32_e32 v111, 0, v111
	v_max_f32_e32 v110, 0, v110
	v_max_f32_e32 v105, 0, v105
	v_max_f32_e32 v104, 0, v104
	v_max_f32_e32 v107, 0, v107
	v_max_f32_e32 v106, 0, v106
	s_cmp_lg_u32 s99, 0
	s_cbranch_scc1 .Lf8nt_1
	global_store_dwordx4 v[114:115], v[118:121], off
	s_branch .Lf8d_1
.Lf8nt_1:
	global_store_dwordx4 v[114:115], v[118:121], off nt
.Lf8d_1:
	v_pk_mul_f32 v[110:111], v[110:111], v[110:111]
	v_pk_mul_f32 v[108:109], v[108:109], v[108:109]
	v_pk_mul_f32 v[114:115], v[106:107], v[106:107]
	v_pk_mul_f32 v[106:107], v[104:105], v[104:105]
	s_nop 7
	v_cvt_pk_bf16_f32 v104, v108, v109
	v_cvt_pk_bf16_f32 v105, v110, v111
	v_cvt_pk_bf16_f32 v106, v106, v107
	v_cvt_pk_bf16_f32 v107, v114, v115
	v_max_f32_e32 v101, 0, v101
	v_max_f32_e32 v100, 0, v100
	v_max_f32_e32 v103, 0, v103
	v_max_f32_e32 v102, 0, v102
	v_max_f32_e32 v97, 0, v97
	v_max_f32_e32 v96, 0, v96
	v_max_f32_e32 v99, 0, v99
	v_max_f32_e32 v98, 0, v98
	ds_write_b128 v147, v[104:107]
	v_pk_mul_f32 v[102:103], v[102:103], v[102:103]
	v_pk_mul_f32 v[100:101], v[100:101], v[100:101]
	v_pk_mul_f32 v[104:105], v[98:99], v[98:99]
	v_pk_mul_f32 v[98:99], v[96:97], v[96:97]
	v_cvt_pk_bf16_f32 v96, v100, v101
	v_cvt_pk_bf16_f32 v97, v102, v103
	v_cvt_pk_bf16_f32 v98, v98, v99
	v_cvt_pk_bf16_f32 v99, v104, v105
	ds_write_b128 v147, v[96:99] offset:64
	ds_read_b128 v[96:99], v148
	ds_read_b128 v[100:103], v148 offset:1152
	v_add_co_u32_e32 v104, vcc, s48, v112
	s_nop 0
	s_nop 0
	v_addc_co_u32_e32 v105, vcc, 0, v113, vcc
	s_waitcnt lgkmcnt(0)
	s_cmp_lg_u32 s99, 0
	s_cbranch_scc1 .Lf8nt_2
	global_store_dwordx4 v[104:105], v[96:99], off
	s_branch .Lf8d_2
.Lf8nt_2:
	global_store_dwordx4 v[104:105], v[96:99], off nt
.Lf8d_2:
	s_nop 1
	v_add_co_u32_e32 v96, vcc, s49, v112
	s_nop 4
	v_addc_co_u32_e32 v97, vcc, 0, v113, vcc
	v_max_f32_e32 v93, 0, v93
	v_max_f32_e32 v92, 0, v92
	v_max_f32_e32 v95, 0, v95
	v_max_f32_e32 v94, 0, v94
	v_max_f32_e32 v89, 0, v89
	v_max_f32_e32 v88, 0, v88
	v_max_f32_e32 v91, 0, v91
	v_max_f32_e32 v90, 0, v90
	s_cmp_lg_u32 s99, 0
	s_cbranch_scc1 .Lf8nt_3
	global_store_dwordx4 v[96:97], v[100:103], off
	s_branch .Lf8d_3
.Lf8nt_3:
	global_store_dwordx4 v[96:97], v[100:103], off nt
.Lf8d_3:
	v_pk_mul_f32 v[94:95], v[94:95], v[94:95]
	v_pk_mul_f32 v[92:93], v[92:93], v[92:93]
	v_pk_mul_f32 v[96:97], v[90:91], v[90:91]
	v_pk_mul_f32 v[90:91], v[88:89], v[88:89]
	s_nop 7
	v_cvt_pk_bf16_f32 v88, v92, v93
	v_cvt_pk_bf16_f32 v89, v94, v95
	v_cvt_pk_bf16_f32 v90, v90, v91
	v_cvt_pk_bf16_f32 v91, v96, v97
	v_max_f32_e32 v85, 0, v85
	v_max_f32_e32 v84, 0, v84
	v_max_f32_e32 v87, 0, v87
	v_max_f32_e32 v86, 0, v86
	v_max_f32_e32 v81, 0, v81
	v_max_f32_e32 v80, 0, v80
	v_max_f32_e32 v83, 0, v83
	v_max_f32_e32 v82, 0, v82
	ds_write_b128 v147, v[88:91]
	v_pk_mul_f32 v[86:87], v[86:87], v[86:87]
	v_pk_mul_f32 v[84:85], v[84:85], v[84:85]
	v_pk_mul_f32 v[88:89], v[82:83], v[82:83]
	v_pk_mul_f32 v[82:83], v[80:81], v[80:81]
	v_cvt_pk_bf16_f32 v80, v84, v85
	v_cvt_pk_bf16_f32 v81, v86, v87
	v_cvt_pk_bf16_f32 v82, v82, v83
	v_cvt_pk_bf16_f32 v83, v88, v89
	ds_write_b128 v147, v[80:83] offset:64
	ds_read_b128 v[80:83], v148
	ds_read_b128 v[84:87], v148 offset:1152
	v_add_co_u32_e32 v88, vcc, s50, v112
	s_nop 0
	s_nop 0
	v_addc_co_u32_e32 v89, vcc, 0, v113, vcc
	s_waitcnt lgkmcnt(0)
	s_cmp_lg_u32 s99, 0
	s_cbranch_scc1 .Lf8nt_4
	global_store_dwordx4 v[88:89], v[80:83], off
	s_branch .Lf8d_4
.Lf8nt_4:
	global_store_dwordx4 v[88:89], v[80:83], off nt
.Lf8d_4:
	s_nop 1
	v_add_co_u32_e32 v80, vcc, s51, v112
	s_nop 4
	v_addc_co_u32_e32 v81, vcc, 0, v113, vcc
	v_max_f32_e32 v77, 0, v77
	v_max_f32_e32 v76, 0, v76
	v_max_f32_e32 v79, 0, v79
	v_max_f32_e32 v78, 0, v78
	v_max_f32_e32 v73, 0, v73
	v_max_f32_e32 v72, 0, v72
	v_max_f32_e32 v75, 0, v75
	v_max_f32_e32 v74, 0, v74
	s_cmp_lg_u32 s99, 0
	s_cbranch_scc1 .Lf8nt_5
	global_store_dwordx4 v[80:81], v[84:87], off
	s_branch .Lf8d_5
.Lf8nt_5:
	global_store_dwordx4 v[80:81], v[84:87], off nt
.Lf8d_5:
	v_pk_mul_f32 v[78:79], v[78:79], v[78:79]
	v_pk_mul_f32 v[76:77], v[76:77], v[76:77]
	v_pk_mul_f32 v[80:81], v[74:75], v[74:75]
	v_pk_mul_f32 v[74:75], v[72:73], v[72:73]
	s_nop 7
	v_cvt_pk_bf16_f32 v72, v76, v77
	v_cvt_pk_bf16_f32 v73, v78, v79
	v_cvt_pk_bf16_f32 v74, v74, v75
	v_cvt_pk_bf16_f32 v75, v80, v81
	v_max_f32_e32 v69, 0, v69
	v_max_f32_e32 v68, 0, v68
	v_max_f32_e32 v71, 0, v71
	v_max_f32_e32 v70, 0, v70
	v_max_f32_e32 v65, 0, v65
	v_max_f32_e32 v64, 0, v64
	v_max_f32_e32 v67, 0, v67
	v_max_f32_e32 v66, 0, v66
	ds_write_b128 v147, v[72:75]
	v_pk_mul_f32 v[70:71], v[70:71], v[70:71]
	v_pk_mul_f32 v[68:69], v[68:69], v[68:69]
	v_pk_mul_f32 v[72:73], v[66:67], v[66:67]
	v_pk_mul_f32 v[66:67], v[64:65], v[64:65]
	v_cvt_pk_bf16_f32 v64, v68, v69
	v_cvt_pk_bf16_f32 v65, v70, v71
	v_cvt_pk_bf16_f32 v66, v66, v67
	v_cvt_pk_bf16_f32 v67, v72, v73
	ds_write_b128 v147, v[64:67] offset:64
	ds_read_b128 v[64:67], v148
	ds_read_b128 v[68:71], v148 offset:1152
	v_add_co_u32_e32 v72, vcc, s52, v112
	s_nop 0
	s_nop 0
	v_addc_co_u32_e32 v73, vcc, 0, v113, vcc
	s_waitcnt lgkmcnt(0)
	s_cmp_lg_u32 s99, 0
	s_cbranch_scc1 .Lf8nt_6
	global_store_dwordx4 v[72:73], v[64:67], off
	s_branch .Lf8d_6
.Lf8nt_6:
	global_store_dwordx4 v[72:73], v[64:67], off nt
.Lf8d_6:
	s_nop 1
	v_add_co_u32_e32 v64, vcc, s53, v112
	s_nop 4
	v_addc_co_u32_e32 v65, vcc, 0, v113, vcc
	v_max_f32_e32 v61, 0, v61
	v_max_f32_e32 v60, 0, v60
	v_max_f32_e32 v63, 0, v63
	v_max_f32_e32 v62, 0, v62
	v_max_f32_e32 v57, 0, v57
	v_max_f32_e32 v56, 0, v56
	v_max_f32_e32 v59, 0, v59
	v_max_f32_e32 v58, 0, v58
	s_cmp_lg_u32 s99, 0
	s_cbranch_scc1 .Lf8nt_7
	global_store_dwordx4 v[64:65], v[68:71], off
	s_branch .Lf8d_7
.Lf8nt_7:
	global_store_dwordx4 v[64:65], v[68:71], off nt
.Lf8d_7:
	v_pk_mul_f32 v[62:63], v[62:63], v[62:63]
	v_pk_mul_f32 v[60:61], v[60:61], v[60:61]
	v_pk_mul_f32 v[64:65], v[58:59], v[58:59]
	v_pk_mul_f32 v[58:59], v[56:57], v[56:57]
	s_nop 7
	v_cvt_pk_bf16_f32 v56, v60, v61
	v_cvt_pk_bf16_f32 v57, v62, v63
	v_cvt_pk_bf16_f32 v58, v58, v59
	v_cvt_pk_bf16_f32 v59, v64, v65
	v_max_f32_e32 v53, 0, v53
	v_max_f32_e32 v52, 0, v52
	v_max_f32_e32 v55, 0, v55
	v_max_f32_e32 v54, 0, v54
	v_max_f32_e32 v49, 0, v49
	v_max_f32_e32 v48, 0, v48
	v_max_f32_e32 v51, 0, v51
	v_max_f32_e32 v50, 0, v50
	ds_write_b128 v147, v[56:59]
	v_pk_mul_f32 v[54:55], v[54:55], v[54:55]
	v_pk_mul_f32 v[52:53], v[52:53], v[52:53]
	v_pk_mul_f32 v[56:57], v[50:51], v[50:51]
	v_pk_mul_f32 v[50:51], v[48:49], v[48:49]
	v_cvt_pk_bf16_f32 v48, v52, v53
	v_cvt_pk_bf16_f32 v49, v54, v55
	v_cvt_pk_bf16_f32 v50, v50, v51
	v_cvt_pk_bf16_f32 v51, v56, v57
	ds_write_b128 v147, v[48:51] offset:64
	ds_read_b128 v[48:51], v148
	ds_read_b128 v[52:55], v148 offset:1152
	v_add_co_u32_e32 v56, vcc, s54, v112
	s_nop 0
	s_nop 0
	v_addc_co_u32_e32 v57, vcc, 0, v113, vcc
	s_waitcnt lgkmcnt(0)
	s_cmp_lg_u32 s99, 0
	s_cbranch_scc1 .Lf8nt_8
	global_store_dwordx4 v[56:57], v[48:51], off
	s_branch .Lf8d_8
.Lf8nt_8:
	global_store_dwordx4 v[56:57], v[48:51], off nt
.Lf8d_8:
	s_nop 1
	v_add_co_u32_e32 v48, vcc, s55, v112
	s_nop 4
	v_addc_co_u32_e32 v49, vcc, 0, v113, vcc
	v_max_f32_e32 v45, 0, v45
	v_max_f32_e32 v44, 0, v44
	v_max_f32_e32 v47, 0, v47
	v_max_f32_e32 v46, 0, v46
	v_max_f32_e32 v41, 0, v41
	v_max_f32_e32 v40, 0, v40
	v_max_f32_e32 v43, 0, v43
	v_max_f32_e32 v42, 0, v42
	s_cmp_lg_u32 s99, 0
	s_cbranch_scc1 .Lf8nt_9
	global_store_dwordx4 v[48:49], v[52:55], off
	s_branch .Lf8d_9
.Lf8nt_9:
	global_store_dwordx4 v[48:49], v[52:55], off nt
.Lf8d_9:
	v_pk_mul_f32 v[46:47], v[46:47], v[46:47]
	v_pk_mul_f32 v[44:45], v[44:45], v[44:45]
	v_pk_mul_f32 v[48:49], v[42:43], v[42:43]
	v_pk_mul_f32 v[42:43], v[40:41], v[40:41]
	s_nop 7
	v_cvt_pk_bf16_f32 v40, v44, v45
	v_cvt_pk_bf16_f32 v41, v46, v47
	v_cvt_pk_bf16_f32 v42, v42, v43
	v_cvt_pk_bf16_f32 v43, v48, v49
	v_max_f32_e32 v37, 0, v37
	v_max_f32_e32 v36, 0, v36
	v_max_f32_e32 v39, 0, v39
	v_max_f32_e32 v38, 0, v38
	v_max_f32_e32 v33, 0, v33
	v_max_f32_e32 v32, 0, v32
	v_max_f32_e32 v35, 0, v35
	v_max_f32_e32 v34, 0, v34
	ds_write_b128 v147, v[40:43]
	v_pk_mul_f32 v[38:39], v[38:39], v[38:39]
	v_pk_mul_f32 v[36:37], v[36:37], v[36:37]
	v_pk_mul_f32 v[40:41], v[34:35], v[34:35]
	v_pk_mul_f32 v[34:35], v[32:33], v[32:33]
	v_cvt_pk_bf16_f32 v32, v36, v37
	v_cvt_pk_bf16_f32 v33, v38, v39
	v_cvt_pk_bf16_f32 v34, v34, v35
	v_cvt_pk_bf16_f32 v35, v40, v41
	ds_write_b128 v147, v[32:35] offset:64
	ds_read_b128 v[32:35], v148
	ds_read_b128 v[36:39], v148 offset:1152
	v_add_co_u32_e32 v40, vcc, s56, v112
	s_nop 0
	s_nop 0
	v_addc_co_u32_e32 v41, vcc, 0, v113, vcc
	s_waitcnt lgkmcnt(0)
	s_cmp_lg_u32 s99, 0
	s_cbranch_scc1 .Lf8nt_10
	global_store_dwordx4 v[40:41], v[32:35], off
	s_branch .Lf8d_10
.Lf8nt_10:
	global_store_dwordx4 v[40:41], v[32:35], off nt
.Lf8d_10:
	s_nop 1
	v_add_co_u32_e32 v32, vcc, s57, v112
	s_nop 4
	v_addc_co_u32_e32 v33, vcc, 0, v113, vcc
	v_max_f32_e32 v29, 0, v29
	v_max_f32_e32 v28, 0, v28
	v_max_f32_e32 v31, 0, v31
	v_max_f32_e32 v30, 0, v30
	v_max_f32_e32 v25, 0, v25
	v_max_f32_e32 v24, 0, v24
	v_max_f32_e32 v27, 0, v27
	v_max_f32_e32 v26, 0, v26
	s_cmp_lg_u32 s99, 0
	s_cbranch_scc1 .Lf8nt_11
	global_store_dwordx4 v[32:33], v[36:39], off
	s_branch .Lf8d_11
.Lf8nt_11:
	global_store_dwordx4 v[32:33], v[36:39], off nt
.Lf8d_11:
	v_pk_mul_f32 v[30:31], v[30:31], v[30:31]
	v_pk_mul_f32 v[28:29], v[28:29], v[28:29]
	v_pk_mul_f32 v[32:33], v[26:27], v[26:27]
	v_pk_mul_f32 v[26:27], v[24:25], v[24:25]
	s_nop 7
	v_cvt_pk_bf16_f32 v24, v28, v29
	v_cvt_pk_bf16_f32 v25, v30, v31
	v_cvt_pk_bf16_f32 v26, v26, v27
	v_cvt_pk_bf16_f32 v27, v32, v33
	v_max_f32_e32 v21, 0, v21
	v_max_f32_e32 v20, 0, v20
	v_max_f32_e32 v23, 0, v23
	v_max_f32_e32 v22, 0, v22
	v_max_f32_e32 v17, 0, v17
	v_max_f32_e32 v16, 0, v16
	v_max_f32_e32 v19, 0, v19
	v_max_f32_e32 v18, 0, v18
	ds_write_b128 v147, v[24:27]
	v_pk_mul_f32 v[22:23], v[22:23], v[22:23]
	v_pk_mul_f32 v[20:21], v[20:21], v[20:21]
	v_pk_mul_f32 v[24:25], v[18:19], v[18:19]
	v_pk_mul_f32 v[18:19], v[16:17], v[16:17]
	v_cvt_pk_bf16_f32 v16, v20, v21
	v_cvt_pk_bf16_f32 v17, v22, v23
	v_cvt_pk_bf16_f32 v18, v18, v19
	v_cvt_pk_bf16_f32 v19, v24, v25
	ds_write_b128 v147, v[16:19] offset:64
	ds_read_b128 v[16:19], v148
	ds_read_b128 v[20:23], v148 offset:1152
	v_add_co_u32_e32 v24, vcc, s58, v112
	s_nop 0
	s_nop 0
	v_addc_co_u32_e32 v25, vcc, 0, v113, vcc
	s_waitcnt lgkmcnt(0)
	s_cmp_lg_u32 s99, 0
	s_cbranch_scc1 .Lf8nt_12
	global_store_dwordx4 v[24:25], v[16:19], off
	s_branch .Lf8d_12
.Lf8nt_12:
	global_store_dwordx4 v[24:25], v[16:19], off nt
.Lf8d_12:
	s_nop 1
	v_add_co_u32_e32 v16, vcc, s59, v112
	s_nop 4
	v_addc_co_u32_e32 v17, vcc, 0, v113, vcc
	v_max_f32_e32 v13, 0, v13
	v_max_f32_e32 v12, 0, v12
	v_max_f32_e32 v15, 0, v15
	v_max_f32_e32 v14, 0, v14
	v_max_f32_e32 v9, 0, v9
	v_max_f32_e32 v8, 0, v8
	v_max_f32_e32 v11, 0, v11
	v_max_f32_e32 v10, 0, v10
	s_cmp_lg_u32 s99, 0
	s_cbranch_scc1 .Lf8nt_13
	global_store_dwordx4 v[16:17], v[20:23], off
	s_branch .Lf8d_13
.Lf8nt_13:
	global_store_dwordx4 v[16:17], v[20:23], off nt
.Lf8d_13:
	v_pk_mul_f32 v[14:15], v[14:15], v[14:15]
	v_pk_mul_f32 v[12:13], v[12:13], v[12:13]
	v_pk_mul_f32 v[16:17], v[10:11], v[10:11]
	v_pk_mul_f32 v[10:11], v[8:9], v[8:9]
	s_nop 7
	v_cvt_pk_bf16_f32 v8, v12, v13
	v_cvt_pk_bf16_f32 v9, v14, v15
	v_cvt_pk_bf16_f32 v10, v10, v11
	v_cvt_pk_bf16_f32 v11, v16, v17
	v_max_f32_e32 v5, 0, v5
	v_max_f32_e32 v4, 0, v4
	v_max_f32_e32 v7, 0, v7
	v_max_f32_e32 v6, 0, v6
	v_max_f32_e32 v1, 0, v1
	v_max_f32_e32 v0, 0, v0
	v_max_f32_e32 v3, 0, v3
	v_max_f32_e32 v2, 0, v2
	ds_write_b128 v147, v[8:11]
	v_pk_mul_f32 v[6:7], v[6:7], v[6:7]
	v_pk_mul_f32 v[4:5], v[4:5], v[4:5]
	v_pk_mul_f32 v[8:9], v[2:3], v[2:3]
	v_pk_mul_f32 v[2:3], v[0:1], v[0:1]
	v_cvt_pk_bf16_f32 v0, v4, v5
	v_cvt_pk_bf16_f32 v1, v6, v7
	v_cvt_pk_bf16_f32 v2, v2, v3
	v_cvt_pk_bf16_f32 v3, v8, v9
	ds_write_b128 v147, v[0:3] offset:64
	ds_read_b128 v[0:3], v148
	ds_read_b128 v[4:7], v148 offset:1152
	v_add_co_u32_e32 v8, vcc, 0x160000, v112
	s_nop 1
	v_addc_co_u32_e32 v9, vcc, 0, v113, vcc
	s_waitcnt lgkmcnt(0)
	s_cmp_lg_u32 s99, 0
	s_cbranch_scc1 .Lf8nt_14
	global_store_dwordx4 v[8:9], v[0:3], off
	s_branch .Lf8d_14
.Lf8nt_14:
	global_store_dwordx4 v[8:9], v[0:3], off nt
.Lf8d_14:
	s_nop 1
	v_add_co_u32_e32 v0, vcc, 0x170000, v112
	s_nop 1
	v_addc_co_u32_e32 v1, vcc, 0, v113, vcc
	s_andn2_b64 vcc, exec, s[0:1]
	s_mov_b64 s[0:1], -1
	s_cmp_lg_u32 s99, 0
	s_cbranch_scc1 .Lf8nt_15
	global_store_dwordx4 v[0:1], v[4:7], off
	s_branch .Lf8d_15
.Lf8nt_15:
	global_store_dwordx4 v[0:1], v[4:7], off nt
.Lf8d_15:
	s_cbranch_vccnz .LBB0_891
	s_andn2_b64 vcc, exec, s[10:11]
	s_cbranch_vccnz .LBB0_890
	s_barrier
	s_branch .LBB0_890
